# P7 unit top: wait only for the staged K/V loads, not the previous unit's output stores
# speedup vs baseline: 1.0127x; 1.0127x over previous
.LBB0_638:
	s_waitcnt vmcnt(8) lgkmcnt(0)
	s_barrier
	s_add_i32 s65, s9, s91
	s_cmpk_gt_i32 s65, 0x3ff
	s_cselect_b64 s[58:59], -1, 0
	s_cmpk_lt_i32 s65, 0x400
	s_mov_b64 s[0:1], -1
	s_cbranch_scc1 .LBB0_640
	s_lshl_b32 s66, s64, 16
	s_mov_b64 s[0:1], 0
